# phase-1 modulated RMSNorm row loop hand-rewritten: scalar row addressing, all scale/shift loads issued up front, next-row x prefetch (x2 unroll), norm_gain loaded once; same arithmetic order
# baseline (speedup 1.0000x reference)
; DI int opaque(int v) { asm volatile("" : "+v"(v)); return v; }
; DI void phase1(const Params& p, char* sm) {
;     const int tt_ = opaque(threadIdx.x), lane = tt_ & 63, w = tt_ >> 6;
;     const float* mod = (const float*)(p.ws + WS_MOD);
;     u16* H = (u16*)(p.ws + WS_H);
;     for (int row = blockIdx.x * 4 + w; row < NT; row += gridDim.x * 4) {
;         const float* xr = row < NP ? p.x_p + (size_t)row * 1024 : p.x_s + (size_t)(row - NP) * 1024;
;         const int mb = row < NP ? (row >> 13) : 2 + ((row - NP) >> 2);
;         f32x4 v[4]; float ss = 0.f;
; #pragma unroll
;         for (int j = 0; j < 4; ++j) { v[j] = *(const f32x4*)(xr + lane * 4 + 256 * j); ss += v[j].x * v[j].x + v[j].y * v[j].y + v[j].z * v[j].z + v[j].w * v[j].w; }
;         ss = wave_sum(ss);
;         const float inv = rsqrtf(ss * (1.f / 1024.f) + 1e-6f);
; #pragma unroll
;         for (int j = 0; j < 4; ++j) {
;             const int col = lane * 4 + 256 * j;
;             const f32x4 g = *(const f32x4*)(p.norm_gain + col);
;             const f32x4 sh = *(const f32x4*)(mod + mb * 3072 + col);
;             const f32x4 sc = *(const f32x4*)(mod + mb * 3072 + 1024 + col);
;             const float h0 = (v[j].x * inv) * g.x * (1.f + sc.x) + sh.x;
;             const float h1 = (v[j].y * inv) * g.y * (1.f + sc.y) + sh.y;
;             const float h2 = (v[j].z * inv) * g.z * (1.f + sc.z) + sh.z;
;             const float h3 = (v[j].w * inv) * g.w * (1.f + sc.w) + sh.w;
;             *(uint2*)(H + (size_t)row * 1024 + col) = cvt4(h0, h1, h2, h3);
;         }
;     }
.LBB0_167:
	s_or_b64 exec, exec, s[2:3]
	v_mov_b32_e32 v3, v0
	s_add_u32 s6, s62, 0xdb6000
	s_waitcnt lgkmcnt(0)
	s_barrier
	s_addc_u32 s7, s63, 0
	v_ashrrev_i32_e32 v1, 6, v3
	s_lshl_b32 s2, s80, 2
	v_writelane_b32 v254, s2, 10
	v_add_u32_e32 v2, s2, v1
	s_movk_i32 s2, 0x4080
	v_cmp_gt_i32_e32 vcc, s2, v2
	v_mbcnt_lo_u32_b32 v1, -1, 0
	s_and_saveexec_b64 s[2:3], vcc
	s_cbranch_execz .LBB0_174
	v_lshlrev_b32_e32 v3, 2, v3
	v_and_b32_e32 v10, 0xfc, v3
	v_mbcnt_hi_u32_b32 v3, -1, v1
	v_and_b32_e32 v4, 64, v3
	v_add_u32_e32 v4, 64, v4
	v_xor_b32_e32 v6, 1, v3
	v_cmp_lt_i32_e32 vcc, v6, v4
	s_load_dword s4, s[0:1], 0xb0
	v_mov_b32_e32 v5, 0
	v_cndmask_b32_e32 v6, v3, v6, vcc
	v_lshlrev_b32_e32 v20, 2, v6
	v_xor_b32_e32 v6, 2, v3
	v_cmp_lt_i32_e32 vcc, v6, v4
	s_add_u32 s8, s62, 0x8000
	v_or_b32_e32 v12, 0x100, v10
	v_cndmask_b32_e32 v6, v3, v6, vcc
	v_lshlrev_b32_e32 v21, 2, v6
	v_xor_b32_e32 v6, 4, v3
	v_cmp_lt_i32_e32 vcc, v6, v4
	v_or_b32_e32 v14, 0x200, v10
	v_or_b32_e32 v16, 0x300, v10
	v_cndmask_b32_e32 v6, v3, v6, vcc
	v_lshlrev_b32_e32 v22, 2, v6
	v_xor_b32_e32 v6, 8, v3
	v_cmp_lt_i32_e32 vcc, v6, v4
	s_addc_u32 s9, s63, 0
	s_waitcnt lgkmcnt(0)
	s_lshl_b32 s16, s4, 2
	v_cndmask_b32_e32 v6, v3, v6, vcc
	v_lshlrev_b32_e32 v23, 2, v6
	v_xor_b32_e32 v6, 16, v3
	v_cmp_lt_i32_e32 vcc, v6, v4
	s_mov_b64 s[10:11], 0
	s_movk_i32 s17, 0x4000
	v_cndmask_b32_e32 v6, v3, v6, vcc
	v_lshlrev_b32_e32 v24, 2, v6
	v_xor_b32_e32 v6, 32, v3
	v_cmp_lt_i32_e32 vcc, v6, v4
	v_lshlrev_b32_e32 v4, 2, v10
	s_movk_i32 s18, 0x3fff
	v_cndmask_b32_e32 v3, v3, v6, vcc
	v_lshl_add_u64 v[6:7], s[20:21], 0, v[4:5]
	v_lshlrev_b32_e32 v4, 1, v10
	v_lshlrev_b32_e32 v25, 2, v3
	v_lshl_add_u64 v[8:9], s[6:7], 0, v[4:5]
	v_lshlrev_b32_e32 v10, 2, v10
	v_mov_b32_e32 v11, v5
	v_mov_b32_e32 v26, 0x358637bd
	s_mov_b32 s19, 0x800000
	s_movk_i32 s20, 0xc00
	s_mov_b64 s[12:13], 0x1000
	v_lshlrev_b32_e32 v12, 2, v12
	v_mov_b32_e32 v13, v5
	v_lshlrev_b32_e32 v14, 2, v14
	v_mov_b32_e32 v15, v5
	v_lshlrev_b32_e32 v16, 2, v16
	v_mov_b32_e32 v17, v5
	s_movk_i32 s21, 0x407f
	global_load_dwordx4 v[98:101], v[6:7], off
	global_load_dwordx4 v[102:105], v[6:7], off offset:1024
	global_load_dwordx4 v[106:109], v[6:7], off offset:2048
	global_load_dwordx4 v[110:113], v[6:7], off offset:3072
	v_lshrrev_b32_e32 v130, 1, v10
	v_readfirstlane_b32 s64, v2
	s_sub_i32 s78, s64, 0x4000
	s_cmp_lt_i32 s64, 0x4000
	s_cselect_b32 s78, s64, s78
	s_cselect_b32 s76, s36, s38
	s_cselect_b32 s77, s37, s39
	s_mov_b32 s79, 0
	s_lshl_b64 s[78:79], s[78:79], 12
	s_add_u32 s66, s76, s78
	s_addc_u32 s67, s77, s79
	global_load_dwordx4 v[28:31], v10, s[66:67]
	global_load_dwordx4 v[32:35], v10, s[66:67] offset:1024
	global_load_dwordx4 v[36:39], v10, s[66:67] offset:2048
	global_load_dwordx4 v[40:43], v10, s[66:67] offset:3072
.Lp1_A:
	s_sub_i32 s74, s64, 0x4000
	s_lshr_b32 s74, s74, 2
	s_add_i32 s74, s74, 2
	s_lshr_b32 s75, s64, 13
	s_cmp_lt_i32 s64, 0x4000
	s_cselect_b32 s74, s75, s74
	s_mul_i32 s74, s74, 0x3000
	s_add_u32 s68, s8, s74
	s_addc_u32 s69, s9, 0
	s_add_u32 s70, s68, 0x1000
	s_addc_u32 s71, s69, 0
	global_load_dwordx4 v[44:47], v10, s[70:71]
	global_load_dwordx4 v[132:135], v10, s[70:71] offset:1024
	global_load_dwordx4 v[136:139], v10, s[70:71] offset:2048
	global_load_dwordx4 v[140:143], v10, s[70:71] offset:3072
	global_load_dwordx4 v[52:55], v10, s[68:69]
	global_load_dwordx4 v[144:147], v10, s[68:69] offset:1024
	global_load_dwordx4 v[148:151], v10, s[68:69] offset:2048
	global_load_dwordx4 v[152:155], v10, s[68:69] offset:3072
	s_lshl_b32 s72, s64, 11
	s_add_u32 s72, s6, s72
	s_addc_u32 s73, s7, 0
	s_add_i32 s65, s64, s16
	s_cmp_gt_i32 s65, s21
	s_cbranch_scc1 .Lp1_A_nopf
	s_sub_i32 s78, s65, 0x4000
	s_cmp_lt_i32 s65, 0x4000
	s_cselect_b32 s78, s65, s78
	s_cselect_b32 s76, s36, s38
	s_cselect_b32 s77, s37, s39
	s_mov_b32 s79, 0
	s_lshl_b64 s[78:79], s[78:79], 12
	s_add_u32 s66, s76, s78
	s_addc_u32 s67, s77, s79
	global_load_dwordx4 v[114:117], v10, s[66:67]
	global_load_dwordx4 v[118:121], v10, s[66:67] offset:1024
	global_load_dwordx4 v[122:125], v10, s[66:67] offset:2048
	global_load_dwordx4 v[126:129], v10, s[66:67] offset:3072
	s_waitcnt vmcnt(12)
	s_branch .Lp1_A_go
.Lp1_A_nopf:
	s_waitcnt vmcnt(8)
.Lp1_A_go:
	v_mov_b32_e32 v60, v29
	v_mov_b32_e32 v61, v33
	v_mov_b32_e32 v58, v28
	v_mov_b32_e32 v59, v32
	v_mov_b32_e32 v68, v37
	v_mov_b32_e32 v69, v41
	v_pk_mul_f32 v[60:61], v[60:61], v[60:61]
	v_mov_b32_e32 v62, v30
	v_mov_b32_e32 v63, v34
	v_mov_b32_e32 v66, v36
	v_mov_b32_e32 v67, v40
	v_pk_mul_f32 v[68:69], v[68:69], v[68:69]
	v_pk_fma_f32 v[58:59], v[58:59], v[58:59], v[60:61]
	v_mov_b32_e32 v64, v31
	v_mov_b32_e32 v65, v35
	v_mov_b32_e32 v70, v38
	v_mov_b32_e32 v71, v42
	v_pk_fma_f32 v[60:61], v[66:67], v[66:67], v[68:69]
	v_pk_fma_f32 v[58:59], v[62:63], v[62:63], v[58:59]
	v_mov_b32_e32 v72, v39
	v_mov_b32_e32 v73, v43
	v_pk_fma_f32 v[60:61], v[70:71], v[70:71], v[60:61]
	v_pk_fma_f32 v[58:59], v[64:65], v[64:65], v[58:59]
	v_pk_fma_f32 v[60:61], v[72:73], v[72:73], v[60:61]
	v_add_f32_e32 v4, v58, v59
	v_add_f32_e32 v4, v4, v60
	v_add_f32_e32 v4, v4, v61
	ds_bpermute_b32 v27, v20, v4
	s_waitcnt lgkmcnt(0)
	v_add_f32_e32 v4, v4, v27
	ds_bpermute_b32 v27, v21, v4
	s_waitcnt lgkmcnt(0)
	v_add_f32_e32 v4, v4, v27
	ds_bpermute_b32 v27, v22, v4
	s_waitcnt lgkmcnt(0)
	v_add_f32_e32 v4, v4, v27
	ds_bpermute_b32 v27, v23, v4
	s_waitcnt lgkmcnt(0)
	v_add_f32_e32 v4, v4, v27
	ds_bpermute_b32 v27, v24, v4
	s_waitcnt lgkmcnt(0)
	v_add_f32_e32 v4, v4, v27
	ds_bpermute_b32 v27, v25, v4
	s_waitcnt lgkmcnt(0)
	v_add_f32_e32 v3, v4, v27
	v_fmamk_f32 v3, v3, 0x3a800000, v26
	v_mul_f32_e32 v4, 0x4b800000, v3
	v_cmp_gt_f32_e32 vcc, s19, v3
	s_nop 1
	v_cndmask_b32_e32 v3, v3, v4, vcc
	v_rsq_f32_e32 v3, v3
	s_nop 0
	v_mul_f32_e32 v4, 0x45800000, v3
	v_cndmask_b32_e32 v4, v3, v4, vcc
	v_pk_mul_f32 v[28:29], v[28:29], v[4:5] op_sel_hi:[1,0]
	v_pk_mul_f32 v[30:31], v[30:31], v[4:5] op_sel_hi:[1,0]
	v_pk_mul_f32 v[32:33], v[32:33], v[4:5] op_sel_hi:[1,0]
	v_pk_mul_f32 v[34:35], v[34:35], v[4:5] op_sel_hi:[1,0]
	v_pk_mul_f32 v[36:37], v[36:37], v[4:5] op_sel_hi:[1,0]
	v_pk_mul_f32 v[38:39], v[38:39], v[4:5] op_sel_hi:[1,0]
	v_pk_mul_f32 v[40:41], v[40:41], v[4:5] op_sel_hi:[1,0]
	v_pk_mul_f32 v[42:43], v[42:43], v[4:5] op_sel_hi:[1,0]
	s_cmp_gt_i32 s65, s21
	s_cbranch_scc1 .Lp1_A_w0
	s_waitcnt vmcnt(4)
	s_branch .Lp1_A_w1

; DI void phase1(const Params& p, char* sm) {
;     ...
;     for (int row = blockIdx.x * 4 + w; row < NT; row += gridDim.x * 4) {
;         const float* xr = row < NP ? p.x_p + (size_t)row * 1024 : p.x_s + (size_t)(row - NP) * 1024;
;         const int mb = row < NP ? (row >> 13) : 2 + ((row - NP) >> 2);
;         f32x4 v[4]; float ss = 0.f;
; #pragma unroll
;         for (int j = 0; j < 4; ++j) { v[j] = *(const f32x4*)(xr + lane * 4 + 256 * j); ss += v[j].x * v[j].x + v[j].y * v[j].y + v[j].z * v[j].z + v[j].w * v[j].w; }
;     ...
; #pragma unroll
;         for (int j = 0; j < 4; ++j) {
;             const int col = lane * 4 + 256 * j;
;             const f32x4 g = *(const f32x4*)(p.norm_gain + col);
;             const f32x4 sh = *(const f32x4*)(mod + mb * 3072 + col);
;             const f32x4 sc = *(const f32x4*)(mod + mb * 3072 + 1024 + col);
;             const float h0 = (v[j].x * inv) * g.x * (1.f + sc.x) + sh.x;
;             const float h1 = (v[j].y * inv) * g.y * (1.f + sc.y) + sh.y;
;             const float h2 = (v[j].z * inv) * g.z * (1.f + sc.z) + sh.z;
;             const float h3 = (v[j].w * inv) * g.w * (1.f + sc.w) + sh.w;
;             *(uint2*)(H + (size_t)row * 1024 + col) = cvt4(h0, h1, h2, h3);
;         }
.Lp1_A_w1:
	v_pk_add_f32 v[44:45], v[44:45], 1.0 op_sel_hi:[1,0]
	v_pk_add_f32 v[46:47], v[46:47], 1.0 op_sel_hi:[1,0]
	v_pk_add_f32 v[132:133], v[132:133], 1.0 op_sel_hi:[1,0]
	v_pk_add_f32 v[134:135], v[134:135], 1.0 op_sel_hi:[1,0]
	v_pk_add_f32 v[136:137], v[136:137], 1.0 op_sel_hi:[1,0]
	v_pk_add_f32 v[138:139], v[138:139], 1.0 op_sel_hi:[1,0]
	v_pk_add_f32 v[140:141], v[140:141], 1.0 op_sel_hi:[1,0]
	v_pk_add_f32 v[142:143], v[142:143], 1.0 op_sel_hi:[1,0]
	v_pk_mul_f32 v[28:29], v[98:99], v[28:29]
	v_pk_mul_f32 v[30:31], v[100:101], v[30:31]
	v_pk_mul_f32 v[32:33], v[102:103], v[32:33]
	v_pk_mul_f32 v[34:35], v[104:105], v[34:35]
	v_pk_mul_f32 v[36:37], v[106:107], v[36:37]
	v_pk_mul_f32 v[38:39], v[108:109], v[38:39]
	v_pk_mul_f32 v[40:41], v[110:111], v[40:41]
	v_pk_mul_f32 v[42:43], v[112:113], v[42:43]
	v_pk_fma_f32 v[28:29], v[44:45], v[28:29], v[52:53]
	v_pk_fma_f32 v[30:31], v[46:47], v[30:31], v[54:55]
	v_pk_fma_f32 v[32:33], v[132:133], v[32:33], v[144:145]
	v_pk_fma_f32 v[34:35], v[134:135], v[34:35], v[146:147]
	v_pk_fma_f32 v[36:37], v[136:137], v[36:37], v[148:149]
	v_pk_fma_f32 v[38:39], v[138:139], v[38:39], v[150:151]
	v_pk_fma_f32 v[40:41], v[140:141], v[40:41], v[152:153]
	v_pk_fma_f32 v[42:43], v[142:143], v[42:43], v[154:155]
	v_cvt_pk_bf16_f32 v28, v28, v29
	v_cvt_pk_bf16_f32 v29, v30, v31
	v_cvt_pk_bf16_f32 v30, v32, v33
	v_cvt_pk_bf16_f32 v31, v34, v35
	v_cvt_pk_bf16_f32 v32, v36, v37
	v_cvt_pk_bf16_f32 v33, v38, v39
	v_cvt_pk_bf16_f32 v34, v40, v41
	v_cvt_pk_bf16_f32 v35, v42, v43
	global_store_dwordx2 v130, v[28:29], s[72:73]
	global_store_dwordx2 v130, v[30:31], s[72:73] offset:512
	global_store_dwordx2 v130, v[32:33], s[72:73] offset:1024
	global_store_dwordx2 v130, v[34:35], s[72:73] offset:1536
	s_mov_b32 s64, s65
	s_cmp_gt_i32 s64, s21
	s_cbranch_scc1 .LBB0_174
.Lp1_B:
	s_sub_i32 s74, s64, 0x4000
	s_lshr_b32 s74, s74, 2
	s_add_i32 s74, s74, 2
	s_lshr_b32 s75, s64, 13
	s_cmp_lt_i32 s64, 0x4000
	s_cselect_b32 s74, s75, s74
	s_mul_i32 s74, s74, 0x3000
	s_add_u32 s68, s8, s74
	s_addc_u32 s69, s9, 0
	s_add_u32 s70, s68, 0x1000
	s_addc_u32 s71, s69, 0
	global_load_dwordx4 v[44:47], v10, s[70:71]
	global_load_dwordx4 v[132:135], v10, s[70:71] offset:1024
	global_load_dwordx4 v[136:139], v10, s[70:71] offset:2048
	global_load_dwordx4 v[140:143], v10, s[70:71] offset:3072
	global_load_dwordx4 v[52:55], v10, s[68:69]
	global_load_dwordx4 v[144:147], v10, s[68:69] offset:1024
	global_load_dwordx4 v[148:151], v10, s[68:69] offset:2048
	global_load_dwordx4 v[152:155], v10, s[68:69] offset:3072
	s_lshl_b32 s72, s64, 11
	s_add_u32 s72, s6, s72
	s_addc_u32 s73, s7, 0
	s_add_i32 s65, s64, s16
	s_cmp_gt_i32 s65, s21
	s_cbranch_scc1 .Lp1_B_nopf
	s_sub_i32 s78, s65, 0x4000
	s_cmp_lt_i32 s65, 0x4000
	s_cselect_b32 s78, s65, s78
	s_cselect_b32 s76, s36, s38
	s_cselect_b32 s77, s37, s39
	s_mov_b32 s79, 0
	s_lshl_b64 s[78:79], s[78:79], 12
	s_add_u32 s66, s76, s78
	s_addc_u32 s67, s77, s79
	global_load_dwordx4 v[28:31], v10, s[66:67]
	global_load_dwordx4 v[32:35], v10, s[66:67] offset:1024
	global_load_dwordx4 v[36:39], v10, s[66:67] offset:2048
	global_load_dwordx4 v[40:43], v10, s[66:67] offset:3072
	s_waitcnt vmcnt(12)
	s_branch .Lp1_B_go

; DI void phase1(const Params& p, char* sm) {
;     ...
;         for (int j = 0; j < 4; ++j) { v[j] = *(const f32x4*)(xr + lane * 4 + 256 * j); ss += v[j].x * v[j].x + v[j].y * v[j].y + v[j].z * v[j].z + v[j].w * v[j].w; }
;         ss = wave_sum(ss);
;         const float inv = rsqrtf(ss * (1.f / 1024.f) + 1e-6f);
.Lp1_B_go:
	v_mov_b32_e32 v60, v115
	v_mov_b32_e32 v61, v119
	v_mov_b32_e32 v58, v114
	v_mov_b32_e32 v59, v118
	v_mov_b32_e32 v68, v123
	v_mov_b32_e32 v69, v127
	v_pk_mul_f32 v[60:61], v[60:61], v[60:61]
	v_mov_b32_e32 v62, v116
	v_mov_b32_e32 v63, v120
	v_mov_b32_e32 v66, v122
	v_mov_b32_e32 v67, v126
	v_pk_mul_f32 v[68:69], v[68:69], v[68:69]
	v_pk_fma_f32 v[58:59], v[58:59], v[58:59], v[60:61]
	v_mov_b32_e32 v64, v117
	v_mov_b32_e32 v65, v121
	v_mov_b32_e32 v70, v124
	v_mov_b32_e32 v71, v128
	v_pk_fma_f32 v[60:61], v[66:67], v[66:67], v[68:69]
	v_pk_fma_f32 v[58:59], v[62:63], v[62:63], v[58:59]
	v_mov_b32_e32 v72, v125
	v_mov_b32_e32 v73, v129
	v_pk_fma_f32 v[60:61], v[70:71], v[70:71], v[60:61]
	v_pk_fma_f32 v[58:59], v[64:65], v[64:65], v[58:59]
	v_pk_fma_f32 v[60:61], v[72:73], v[72:73], v[60:61]
	v_add_f32_e32 v4, v58, v59
	v_add_f32_e32 v4, v4, v60
	v_add_f32_e32 v4, v4, v61
	ds_bpermute_b32 v27, v20, v4
	s_waitcnt lgkmcnt(0)
	v_add_f32_e32 v4, v4, v27
	ds_bpermute_b32 v27, v21, v4
	s_waitcnt lgkmcnt(0)
	v_add_f32_e32 v4, v4, v27
	ds_bpermute_b32 v27, v22, v4
	s_waitcnt lgkmcnt(0)
	v_add_f32_e32 v4, v4, v27
	ds_bpermute_b32 v27, v23, v4
	s_waitcnt lgkmcnt(0)
	v_add_f32_e32 v4, v4, v27
	ds_bpermute_b32 v27, v24, v4
	s_waitcnt lgkmcnt(0)
	v_add_f32_e32 v4, v4, v27
	ds_bpermute_b32 v27, v25, v4
	s_waitcnt lgkmcnt(0)
	v_add_f32_e32 v3, v4, v27
	v_fmamk_f32 v3, v3, 0x3a800000, v26
	v_mul_f32_e32 v4, 0x4b800000, v3
	v_cmp_gt_f32_e32 vcc, s19, v3
	s_nop 1
	v_cndmask_b32_e32 v3, v3, v4, vcc
	v_rsq_f32_e32 v3, v3
	s_nop 0
	v_mul_f32_e32 v4, 0x45800000, v3
	v_cndmask_b32_e32 v4, v3, v4, vcc
	v_pk_mul_f32 v[114:115], v[114:115], v[4:5] op_sel_hi:[1,0]
	v_pk_mul_f32 v[116:117], v[116:117], v[4:5] op_sel_hi:[1,0]
	v_pk_mul_f32 v[118:119], v[118:119], v[4:5] op_sel_hi:[1,0]
	v_pk_mul_f32 v[120:121], v[120:121], v[4:5] op_sel_hi:[1,0]
	v_pk_mul_f32 v[122:123], v[122:123], v[4:5] op_sel_hi:[1,0]
	v_pk_mul_f32 v[124:125], v[124:125], v[4:5] op_sel_hi:[1,0]
	v_pk_mul_f32 v[126:127], v[126:127], v[4:5] op_sel_hi:[1,0]
	v_pk_mul_f32 v[128:129], v[128:129], v[4:5] op_sel_hi:[1,0]
	s_cmp_gt_i32 s65, s21
	s_cbranch_scc1 .Lp1_B_w0
	s_waitcnt vmcnt(4)
	s_branch .Lp1_B_w1

; DI void phase1(const Params& p, char* sm) {
;     ...
; #pragma unroll
;         for (int j = 0; j < 4; ++j) {
;             const int col = lane * 4 + 256 * j;
;             const f32x4 g = *(const f32x4*)(p.norm_gain + col);
;             const f32x4 sh = *(const f32x4*)(mod + mb * 3072 + col);
;             const f32x4 sc = *(const f32x4*)(mod + mb * 3072 + 1024 + col);
;             const float h0 = (v[j].x * inv) * g.x * (1.f + sc.x) + sh.x;
;             const float h1 = (v[j].y * inv) * g.y * (1.f + sc.y) + sh.y;
;             const float h2 = (v[j].z * inv) * g.z * (1.f + sc.z) + sh.z;
;             const float h3 = (v[j].w * inv) * g.w * (1.f + sc.w) + sh.w;
;             *(uint2*)(H + (size_t)row * 1024 + col) = cvt4(h0, h1, h2, h3);
;         }
.Lp1_B_w1:
	v_pk_add_f32 v[44:45], v[44:45], 1.0 op_sel_hi:[1,0]
	v_pk_add_f32 v[46:47], v[46:47], 1.0 op_sel_hi:[1,0]
	v_pk_add_f32 v[132:133], v[132:133], 1.0 op_sel_hi:[1,0]
	v_pk_add_f32 v[134:135], v[134:135], 1.0 op_sel_hi:[1,0]
	v_pk_add_f32 v[136:137], v[136:137], 1.0 op_sel_hi:[1,0]
	v_pk_add_f32 v[138:139], v[138:139], 1.0 op_sel_hi:[1,0]
	v_pk_add_f32 v[140:141], v[140:141], 1.0 op_sel_hi:[1,0]
	v_pk_add_f32 v[142:143], v[142:143], 1.0 op_sel_hi:[1,0]
	v_pk_mul_f32 v[114:115], v[98:99], v[114:115]
	v_pk_mul_f32 v[116:117], v[100:101], v[116:117]
	v_pk_mul_f32 v[118:119], v[102:103], v[118:119]
	v_pk_mul_f32 v[120:121], v[104:105], v[120:121]
	v_pk_mul_f32 v[122:123], v[106:107], v[122:123]
	v_pk_mul_f32 v[124:125], v[108:109], v[124:125]
	v_pk_mul_f32 v[126:127], v[110:111], v[126:127]
	v_pk_mul_f32 v[128:129], v[112:113], v[128:129]
	v_pk_fma_f32 v[114:115], v[44:45], v[114:115], v[52:53]
	v_pk_fma_f32 v[116:117], v[46:47], v[116:117], v[54:55]
	v_pk_fma_f32 v[118:119], v[132:133], v[118:119], v[144:145]
	v_pk_fma_f32 v[120:121], v[134:135], v[120:121], v[146:147]
	v_pk_fma_f32 v[122:123], v[136:137], v[122:123], v[148:149]
	v_pk_fma_f32 v[124:125], v[138:139], v[124:125], v[150:151]
	v_pk_fma_f32 v[126:127], v[140:141], v[126:127], v[152:153]
	v_pk_fma_f32 v[128:129], v[142:143], v[128:129], v[154:155]
	v_cvt_pk_bf16_f32 v114, v114, v115
	v_cvt_pk_bf16_f32 v115, v116, v117
	v_cvt_pk_bf16_f32 v116, v118, v119
	v_cvt_pk_bf16_f32 v117, v120, v121
	v_cvt_pk_bf16_f32 v118, v122, v123
	v_cvt_pk_bf16_f32 v119, v124, v125
	v_cvt_pk_bf16_f32 v120, v126, v127
	v_cvt_pk_bf16_f32 v121, v128, v129
	global_store_dwordx2 v130, v[114:115], s[72:73]
	global_store_dwordx2 v130, v[116:117], s[72:73] offset:512
	global_store_dwordx2 v130, v[118:119], s[72:73] offset:1024
	global_store_dwordx2 v130, v[120:121], s[72:73] offset:1536
	s_mov_b32 s64, s65
	s_cmp_gt_i32 s64, s21
	s_cbranch_scc1 .LBB0_174
	s_branch .Lp1_A
